# hand-written SwiGLU epilogue (packed scale/add) on top of C=0 peel, default-policy xs stores, de-serialised residual epilogue
# baseline (speedup 1.0000x reference)
; #define PG8_GAS __attribute__((address_space(1)))
; __device__ __forceinline__ unsigned cvtpk(float lo, float hi) { f32x2 v = {lo, hi}; bf16x2_t b = __builtin_convertvector(v, bf16x2_t); return __builtin_bit_cast(unsigned, b); }
; __device__ __forceinline__ float silu_mul(float g, float u) { return g * u * __builtin_amdgcn_rcpf(1.0f + __builtin_amdgcn_exp2f(-1.4426950408889634f * g)); }
;     __device__ __forceinline__ void operator()(const f32x4 (&acc)[2][2][4][2], const Unit& u, int wr, int wc, int fr, int fq) const {
;         const int row0 = u.pm * BM + wr * 64 + fr, col0 = u.pn * HALF + wc * 32 + 8 * fq;
; #pragma unroll
;         for (int ai = 0; ai < 2; ++ai)
; #pragma unroll
;             for (int m = 0; m < 4; ++m) {
;                 bf16_t* p = O + (size_t)(row0 + ai * HALF + m * 16) * ldc + col0;
;                 const f32x4 g0 = acc[ai][0][m][0], g1 = acc[ai][0][m][1], u0 = acc[ai][1][m][0], u1 = acc[ai][1][m][1];
;                 u32x4 w;
;                 w.x = cvtpk(silu_mul(g0[0], u0[0]), silu_mul(g0[1], u0[1])); w.y = cvtpk(silu_mul(g0[2], u0[2]), silu_mul(g0[3], u0[3]));
;                 w.z = cvtpk(silu_mul(g1[0], u1[0]), silu_mul(g1[1], u1[1])); w.w = cvtpk(silu_mul(g1[2], u1[2]), silu_mul(g1[3], u1[3]));
;                 __builtin_nontemporal_store(w, (PG8_GAS u32x4*)p);
;             }
.LBB0_191:
	s_mov_b32 s54, 0xbfb8aa3b
	s_mov_b32 s55, 0xbfb8aa3b
	v_lshl_add_u32 v149, s33, 8, v5
	v_lshl_or_b32 v144, s31, 7, v147
	v_ashrrev_i32_e32 v145, 31, v144
	v_mov_b64_e32 v[142:143], s[6:7]
	v_mad_i64_i32 v[150:151], s[36:37], v149, s93, v[142:143]
	v_lshlrev_b64 v[144:145], 1, v[144:145]
	v_mov_b32_e32 v156, 0x16000
	v_mov_b32_e32 v158, 0x6e000
	v_mov_b32_e32 v157, 0
	v_mov_b32_e32 v159, 0
	v_lshl_add_u64 v[150:151], v[150:151], 0, v[144:145]
	v_pk_mul_f32 v[152:153], v[126:127], s[54:55]
	v_pk_mul_f32 v[154:155], v[128:129], s[54:55]
	v_exp_f32_e32 v152, v152
	v_exp_f32_e32 v153, v153
	v_exp_f32_e32 v154, v154
	v_exp_f32_e32 v155, v155
	v_pk_mul_f32 v[126:127], v[126:127], v[130:131]
	v_pk_mul_f32 v[128:129], v[128:129], v[132:133]
	v_pk_add_f32 v[152:153], v[152:153], 1.0 op_sel_hi:[1,0]
	v_pk_add_f32 v[154:155], v[154:155], 1.0 op_sel_hi:[1,0]
	v_rcp_f32_e32 v152, v152
	v_rcp_f32_e32 v153, v153
	v_rcp_f32_e32 v154, v154
	v_rcp_f32_e32 v155, v155
	v_pk_mul_f32 v[126:127], v[152:153], v[126:127]
	v_pk_mul_f32 v[128:129], v[154:155], v[128:129]
	v_cvt_pk_bf16_f32 v126, v126, v127
	v_cvt_pk_bf16_f32 v127, v128, v129
	v_pk_mul_f32 v[152:153], v[118:119], s[54:55]
	v_pk_mul_f32 v[154:155], v[120:121], s[54:55]
	v_exp_f32_e32 v152, v152
	v_exp_f32_e32 v153, v153
	v_exp_f32_e32 v154, v154
	v_exp_f32_e32 v155, v155
	v_pk_mul_f32 v[118:119], v[118:119], v[122:123]
	v_pk_mul_f32 v[120:121], v[120:121], v[124:125]
	v_pk_add_f32 v[152:153], v[152:153], 1.0 op_sel_hi:[1,0]
	v_pk_add_f32 v[154:155], v[154:155], 1.0 op_sel_hi:[1,0]
	v_rcp_f32_e32 v152, v152
	v_rcp_f32_e32 v153, v153
	v_rcp_f32_e32 v154, v154
	v_rcp_f32_e32 v155, v155
	v_pk_mul_f32 v[118:119], v[152:153], v[118:119]
	v_pk_mul_f32 v[120:121], v[154:155], v[120:121]
	v_cvt_pk_bf16_f32 v128, v118, v119
	v_cvt_pk_bf16_f32 v129, v120, v121
	global_store_dwordx4 v[150:151], v[126:129], off nt
	v_lshl_add_u64 v[150:151], v[150:151], 0, v[156:157]
	v_pk_mul_f32 v[152:153], v[110:111], s[54:55]
	v_pk_mul_f32 v[154:155], v[112:113], s[54:55]
	v_exp_f32_e32 v152, v152
	v_exp_f32_e32 v153, v153
	v_exp_f32_e32 v154, v154
	v_exp_f32_e32 v155, v155
	v_pk_mul_f32 v[110:111], v[110:111], v[114:115]
	v_pk_mul_f32 v[112:113], v[112:113], v[116:117]
	v_pk_add_f32 v[152:153], v[152:153], 1.0 op_sel_hi:[1,0]
	v_pk_add_f32 v[154:155], v[154:155], 1.0 op_sel_hi:[1,0]
	v_rcp_f32_e32 v152, v152
	v_rcp_f32_e32 v153, v153
	v_rcp_f32_e32 v154, v154
	v_rcp_f32_e32 v155, v155
	v_pk_mul_f32 v[110:111], v[152:153], v[110:111]
	v_pk_mul_f32 v[112:113], v[154:155], v[112:113]
	v_cvt_pk_bf16_f32 v110, v110, v111
	v_cvt_pk_bf16_f32 v111, v112, v113
	v_pk_mul_f32 v[152:153], v[102:103], s[54:55]
	v_pk_mul_f32 v[154:155], v[104:105], s[54:55]
	v_exp_f32_e32 v152, v152
	v_exp_f32_e32 v153, v153
	v_exp_f32_e32 v154, v154
	v_exp_f32_e32 v155, v155
	v_pk_mul_f32 v[102:103], v[102:103], v[106:107]
	v_pk_mul_f32 v[104:105], v[104:105], v[108:109]
	v_pk_add_f32 v[152:153], v[152:153], 1.0 op_sel_hi:[1,0]
	v_pk_add_f32 v[154:155], v[154:155], 1.0 op_sel_hi:[1,0]
	v_rcp_f32_e32 v152, v152
	v_rcp_f32_e32 v153, v153
	v_rcp_f32_e32 v154, v154
	v_rcp_f32_e32 v155, v155
	v_pk_mul_f32 v[102:103], v[152:153], v[102:103]
	v_pk_mul_f32 v[104:105], v[154:155], v[104:105]
	v_cvt_pk_bf16_f32 v112, v102, v103
	v_cvt_pk_bf16_f32 v113, v104, v105
	global_store_dwordx4 v[150:151], v[110:113], off nt
	v_lshl_add_u64 v[150:151], v[150:151], 0, v[156:157]
	v_pk_mul_f32 v[152:153], v[94:95], s[54:55]
	v_pk_mul_f32 v[154:155], v[96:97], s[54:55]
	v_exp_f32_e32 v152, v152
	v_exp_f32_e32 v153, v153
	v_exp_f32_e32 v154, v154
	v_exp_f32_e32 v155, v155
	v_pk_mul_f32 v[94:95], v[94:95], v[98:99]
	v_pk_mul_f32 v[96:97], v[96:97], v[100:101]
	v_pk_add_f32 v[152:153], v[152:153], 1.0 op_sel_hi:[1,0]
	v_pk_add_f32 v[154:155], v[154:155], 1.0 op_sel_hi:[1,0]
	v_rcp_f32_e32 v152, v152
	v_rcp_f32_e32 v153, v153
	v_rcp_f32_e32 v154, v154
	v_rcp_f32_e32 v155, v155
	v_pk_mul_f32 v[94:95], v[152:153], v[94:95]
	v_pk_mul_f32 v[96:97], v[154:155], v[96:97]
	v_cvt_pk_bf16_f32 v94, v94, v95
	v_cvt_pk_bf16_f32 v95, v96, v97
	v_pk_mul_f32 v[152:153], v[86:87], s[54:55]
	v_pk_mul_f32 v[154:155], v[88:89], s[54:55]
	v_exp_f32_e32 v152, v152
	v_exp_f32_e32 v153, v153
	v_exp_f32_e32 v154, v154
	v_exp_f32_e32 v155, v155
	v_pk_mul_f32 v[86:87], v[86:87], v[90:91]
	v_pk_mul_f32 v[88:89], v[88:89], v[92:93]
	v_pk_add_f32 v[152:153], v[152:153], 1.0 op_sel_hi:[1,0]
	v_pk_add_f32 v[154:155], v[154:155], 1.0 op_sel_hi:[1,0]
	v_rcp_f32_e32 v152, v152
	v_rcp_f32_e32 v153, v153
	v_rcp_f32_e32 v154, v154
	v_rcp_f32_e32 v155, v155
	v_pk_mul_f32 v[86:87], v[152:153], v[86:87]
	v_pk_mul_f32 v[88:89], v[154:155], v[88:89]
	v_cvt_pk_bf16_f32 v96, v86, v87
	v_cvt_pk_bf16_f32 v97, v88, v89
	global_store_dwordx4 v[150:151], v[94:97], off nt
	v_lshl_add_u64 v[150:151], v[150:151], 0, v[156:157]
	v_pk_mul_f32 v[152:153], v[78:79], s[54:55]
	v_pk_mul_f32 v[154:155], v[80:81], s[54:55]
	v_exp_f32_e32 v152, v152
	v_exp_f32_e32 v153, v153
	v_exp_f32_e32 v154, v154
	v_exp_f32_e32 v155, v155
	v_pk_mul_f32 v[78:79], v[78:79], v[82:83]
	v_pk_mul_f32 v[80:81], v[80:81], v[84:85]
	v_pk_add_f32 v[152:153], v[152:153], 1.0 op_sel_hi:[1,0]
	v_pk_add_f32 v[154:155], v[154:155], 1.0 op_sel_hi:[1,0]
	v_rcp_f32_e32 v152, v152
	v_rcp_f32_e32 v153, v153
	v_rcp_f32_e32 v154, v154
	v_rcp_f32_e32 v155, v155
	v_pk_mul_f32 v[78:79], v[152:153], v[78:79]
	v_pk_mul_f32 v[80:81], v[154:155], v[80:81]
	v_cvt_pk_bf16_f32 v78, v78, v79
	v_cvt_pk_bf16_f32 v79, v80, v81
	v_pk_mul_f32 v[152:153], v[70:71], s[54:55]
	v_pk_mul_f32 v[154:155], v[72:73], s[54:55]
	v_exp_f32_e32 v152, v152
	v_exp_f32_e32 v153, v153
; #define PG8_GAS __attribute__((address_space(1)))
; __device__ __forceinline__ unsigned cvtpk(float lo, float hi) { f32x2 v = {lo, hi}; bf16x2_t b = __builtin_convertvector(v, bf16x2_t); return __builtin_bit_cast(unsigned, b); }
; __device__ __forceinline__ float silu_mul(float g, float u) { return g * u * __builtin_amdgcn_rcpf(1.0f + __builtin_amdgcn_exp2f(-1.4426950408889634f * g)); }
;     __device__ __forceinline__ void operator()(const f32x4 (&acc)[2][2][4][2], const Unit& u, int wr, int wc, int fr, int fq) const {
;     ...
;         for (int ai = 0; ai < 2; ++ai)
; #pragma unroll
;             for (int m = 0; m < 4; ++m) {
;                 bf16_t* p = O + (size_t)(row0 + ai * HALF + m * 16) * ldc + col0;
;                 const f32x4 g0 = acc[ai][0][m][0], g1 = acc[ai][0][m][1], u0 = acc[ai][1][m][0], u1 = acc[ai][1][m][1];
;                 u32x4 w;
;                 w.x = cvtpk(silu_mul(g0[0], u0[0]), silu_mul(g0[1], u0[1])); w.y = cvtpk(silu_mul(g0[2], u0[2]), silu_mul(g0[3], u0[3]));
;                 w.z = cvtpk(silu_mul(g1[0], u1[0]), silu_mul(g1[1], u1[1])); w.w = cvtpk(silu_mul(g1[2], u1[2]), silu_mul(g1[3], u1[3]));
;                 __builtin_nontemporal_store(w, (PG8_GAS u32x4*)p);
;             }
	v_exp_f32_e32 v154, v154
	v_exp_f32_e32 v155, v155
	v_pk_mul_f32 v[70:71], v[70:71], v[74:75]
	v_pk_mul_f32 v[72:73], v[72:73], v[76:77]
	v_pk_add_f32 v[152:153], v[152:153], 1.0 op_sel_hi:[1,0]
	v_pk_add_f32 v[154:155], v[154:155], 1.0 op_sel_hi:[1,0]
	v_rcp_f32_e32 v152, v152
	v_rcp_f32_e32 v153, v153
	v_rcp_f32_e32 v154, v154
	v_rcp_f32_e32 v155, v155
	v_pk_mul_f32 v[70:71], v[152:153], v[70:71]
	v_pk_mul_f32 v[72:73], v[154:155], v[72:73]
	v_cvt_pk_bf16_f32 v80, v70, v71
	v_cvt_pk_bf16_f32 v81, v72, v73
	global_store_dwordx4 v[150:151], v[78:81], off nt
	v_lshl_add_u64 v[150:151], v[150:151], 0, v[158:159]
	v_pk_mul_f32 v[152:153], v[62:63], s[54:55]
	v_pk_mul_f32 v[154:155], v[64:65], s[54:55]
	v_exp_f32_e32 v152, v152
	v_exp_f32_e32 v153, v153
	v_exp_f32_e32 v154, v154
	v_exp_f32_e32 v155, v155
	v_pk_mul_f32 v[62:63], v[62:63], v[66:67]
	v_pk_mul_f32 v[64:65], v[64:65], v[68:69]
	v_pk_add_f32 v[152:153], v[152:153], 1.0 op_sel_hi:[1,0]
	v_pk_add_f32 v[154:155], v[154:155], 1.0 op_sel_hi:[1,0]
	v_rcp_f32_e32 v152, v152
	v_rcp_f32_e32 v153, v153
	v_rcp_f32_e32 v154, v154
	v_rcp_f32_e32 v155, v155
	v_pk_mul_f32 v[62:63], v[152:153], v[62:63]
	v_pk_mul_f32 v[64:65], v[154:155], v[64:65]
	v_cvt_pk_bf16_f32 v62, v62, v63
	v_cvt_pk_bf16_f32 v63, v64, v65
	v_pk_mul_f32 v[152:153], v[54:55], s[54:55]
	v_pk_mul_f32 v[154:155], v[56:57], s[54:55]
	v_exp_f32_e32 v152, v152
	v_exp_f32_e32 v153, v153
	v_exp_f32_e32 v154, v154
	v_exp_f32_e32 v155, v155
	v_pk_mul_f32 v[54:55], v[54:55], v[58:59]
	v_pk_mul_f32 v[56:57], v[56:57], v[60:61]
	v_pk_add_f32 v[152:153], v[152:153], 1.0 op_sel_hi:[1,0]
	v_pk_add_f32 v[154:155], v[154:155], 1.0 op_sel_hi:[1,0]
	v_rcp_f32_e32 v152, v152
	v_rcp_f32_e32 v153, v153
	v_rcp_f32_e32 v154, v154
	v_rcp_f32_e32 v155, v155
	v_pk_mul_f32 v[54:55], v[152:153], v[54:55]
	v_pk_mul_f32 v[56:57], v[154:155], v[56:57]
	v_cvt_pk_bf16_f32 v64, v54, v55
	v_cvt_pk_bf16_f32 v65, v56, v57
	global_store_dwordx4 v[150:151], v[62:65], off nt
	v_lshl_add_u64 v[150:151], v[150:151], 0, v[156:157]
	v_pk_mul_f32 v[152:153], v[46:47], s[54:55]
	v_pk_mul_f32 v[154:155], v[48:49], s[54:55]
	v_exp_f32_e32 v152, v152
	v_exp_f32_e32 v153, v153
	v_exp_f32_e32 v154, v154
	v_exp_f32_e32 v155, v155
	v_pk_mul_f32 v[46:47], v[46:47], v[50:51]
	v_pk_mul_f32 v[48:49], v[48:49], v[52:53]
	v_pk_add_f32 v[152:153], v[152:153], 1.0 op_sel_hi:[1,0]
	v_pk_add_f32 v[154:155], v[154:155], 1.0 op_sel_hi:[1,0]
	v_rcp_f32_e32 v152, v152
	v_rcp_f32_e32 v153, v153
	v_rcp_f32_e32 v154, v154
	v_rcp_f32_e32 v155, v155
	v_pk_mul_f32 v[46:47], v[152:153], v[46:47]
	v_pk_mul_f32 v[48:49], v[154:155], v[48:49]
	v_cvt_pk_bf16_f32 v46, v46, v47
	v_cvt_pk_bf16_f32 v47, v48, v49
	v_pk_mul_f32 v[152:153], v[38:39], s[54:55]
	v_pk_mul_f32 v[154:155], v[40:41], s[54:55]
	v_exp_f32_e32 v152, v152
	v_exp_f32_e32 v153, v153
	v_exp_f32_e32 v154, v154
	v_exp_f32_e32 v155, v155
	v_pk_mul_f32 v[38:39], v[38:39], v[42:43]
	v_pk_mul_f32 v[40:41], v[40:41], v[44:45]
	v_pk_add_f32 v[152:153], v[152:153], 1.0 op_sel_hi:[1,0]
	v_pk_add_f32 v[154:155], v[154:155], 1.0 op_sel_hi:[1,0]
	v_rcp_f32_e32 v152, v152
	v_rcp_f32_e32 v153, v153
	v_rcp_f32_e32 v154, v154
	v_rcp_f32_e32 v155, v155
	v_pk_mul_f32 v[38:39], v[152:153], v[38:39]
	v_pk_mul_f32 v[40:41], v[154:155], v[40:41]
	v_cvt_pk_bf16_f32 v48, v38, v39
	v_cvt_pk_bf16_f32 v49, v40, v41
	global_store_dwordx4 v[150:151], v[46:49], off nt
	v_lshl_add_u64 v[150:151], v[150:151], 0, v[156:157]
	v_pk_mul_f32 v[152:153], v[30:31], s[54:55]
	v_pk_mul_f32 v[154:155], v[32:33], s[54:55]
	v_exp_f32_e32 v152, v152
	v_exp_f32_e32 v153, v153
	v_exp_f32_e32 v154, v154
	v_exp_f32_e32 v155, v155
	v_pk_mul_f32 v[30:31], v[30:31], v[34:35]
	v_pk_mul_f32 v[32:33], v[32:33], v[36:37]
	v_pk_add_f32 v[152:153], v[152:153], 1.0 op_sel_hi:[1,0]
	v_pk_add_f32 v[154:155], v[154:155], 1.0 op_sel_hi:[1,0]
	v_rcp_f32_e32 v152, v152
	v_rcp_f32_e32 v153, v153
	v_rcp_f32_e32 v154, v154
	v_rcp_f32_e32 v155, v155
	v_pk_mul_f32 v[30:31], v[152:153], v[30:31]
	v_pk_mul_f32 v[32:33], v[154:155], v[32:33]
	v_cvt_pk_bf16_f32 v30, v30, v31
	v_cvt_pk_bf16_f32 v31, v32, v33
	v_pk_mul_f32 v[152:153], v[22:23], s[54:55]
	v_pk_mul_f32 v[154:155], v[24:25], s[54:55]
	v_exp_f32_e32 v152, v152
	v_exp_f32_e32 v153, v153
	v_exp_f32_e32 v154, v154
	v_exp_f32_e32 v155, v155
	v_pk_mul_f32 v[22:23], v[22:23], v[26:27]
	v_pk_mul_f32 v[24:25], v[24:25], v[28:29]
	v_pk_add_f32 v[152:153], v[152:153], 1.0 op_sel_hi:[1,0]
	v_pk_add_f32 v[154:155], v[154:155], 1.0 op_sel_hi:[1,0]
	v_rcp_f32_e32 v152, v152
	v_rcp_f32_e32 v153, v153
	v_rcp_f32_e32 v154, v154
	v_rcp_f32_e32 v155, v155
	v_pk_mul_f32 v[22:23], v[152:153], v[22:23]
	v_pk_mul_f32 v[24:25], v[154:155], v[24:25]
	v_cvt_pk_bf16_f32 v32, v22, v23
	v_cvt_pk_bf16_f32 v33, v24, v25
	global_store_dwordx4 v[150:151], v[30:33], off nt
	v_lshl_add_u64 v[150:151], v[150:151], 0, v[156:157]
	v_pk_mul_f32 v[152:153], v[14:15], s[54:55]
	v_pk_mul_f32 v[154:155], v[16:17], s[54:55]
	v_exp_f32_e32 v152, v152
	v_exp_f32_e32 v153, v153
	v_exp_f32_e32 v154, v154
	v_exp_f32_e32 v155, v155
	v_pk_mul_f32 v[14:15], v[14:15], v[18:19]
	v_pk_mul_f32 v[16:17], v[16:17], v[20:21]
	v_pk_add_f32 v[152:153], v[152:153], 1.0 op_sel_hi:[1,0]
	v_pk_add_f32 v[154:155], v[154:155], 1.0 op_sel_hi:[1,0]
	v_rcp_f32_e32 v152, v152
	v_rcp_f32_e32 v153, v153
	v_rcp_f32_e32 v154, v154
	v_rcp_f32_e32 v155, v155
	v_pk_mul_f32 v[14:15], v[152:153], v[14:15]
	v_pk_mul_f32 v[16:17], v[154:155], v[16:17]
	v_cvt_pk_bf16_f32 v14, v14, v15
	v_cvt_pk_bf16_f32 v15, v16, v17
	v_pk_mul_f32 v[152:153], v[10:11], s[54:55]
	v_pk_mul_f32 v[154:155], v[12:13], s[54:55]
	v_exp_f32_e32 v152, v152
	v_exp_f32_e32 v153, v153
	v_exp_f32_e32 v154, v154
	v_exp_f32_e32 v155, v155
	v_pk_mul_f32 v[10:11], v[10:11], v[6:7]
	v_pk_mul_f32 v[12:13], v[12:13], v[8:9]
	v_pk_add_f32 v[152:153], v[152:153], 1.0 op_sel_hi:[1,0]
	v_pk_add_f32 v[154:155], v[154:155], 1.0 op_sel_hi:[1,0]
	v_rcp_f32_e32 v152, v152
	v_rcp_f32_e32 v153, v153
	v_rcp_f32_e32 v154, v154
	v_rcp_f32_e32 v155, v155
	v_pk_mul_f32 v[10:11], v[152:153], v[10:11]
	v_pk_mul_f32 v[12:13], v[154:155], v[12:13]
	v_cvt_pk_bf16_f32 v16, v10, v11
	v_cvt_pk_bf16_f32 v17, v12, v13
	global_store_dwordx4 v[150:151], v[14:17], off nt
	s_mov_b64 s[82:83], -1
	s_andn2_b64 vcc, exec, s[4:5]
	s_cbranch_vccnz .LBB0_184
	s_andn2_b64 vcc, exec, s[70:71]
	s_cbranch_vccnz .LBB0_183
	s_barrier
	s_branch .LBB0_183
